# odd attention: context K/V blocks staged once per unit in LDS by LDS-DMA and shared by the 8 waves (plus the hand-scheduled block loop)
# speedup vs baseline: 1.0191x; 1.0082x over previous
.LBB0_1097:
	s_lshr_b32 s1, s90, 6
	s_and_b32 s1, s1, 15
	s_and_b32 s17, s90, 63
	s_waitcnt lgkmcnt(0)
	s_ashr_i32 s28, s90, 10
	s_lshl_b32 s16, s1, 3
	s_lshl_b32 s1, s28, 12
	s_lshl_b32 s2, s17, 6
	s_or_b32 s1, s1, s2
	v_or_b32_e32 v172, s1, v174
	v_mov_b64_e32 v[0:1], s[22:23]
	v_mad_i64_i32 v[0:1], s[4:5], v172, s48, v[0:1]
	s_lshl_b32 s20, s33, 7
	v_lshl_add_u64 v[0:1], v[0:1], 0, s[20:21]
	v_lshl_add_u64 v[0:1], v[162:163], 1, v[0:1]
	s_waitcnt lgkmcnt(0)
	v_add_co_u32_e32 v2, vcc, s49, v0
	s_lshl_b32 s4, s28, 4
	s_nop 0
	v_addc_co_u32_e32 v3, vcc, 0, v1, vcc
	global_load_dwordx4 v[96:99], v[0:1], off
	global_load_dwordx4 v[100:103], v[0:1], off offset:32
	global_load_dwordx4 v[104:107], v[2:3], off
	global_load_dwordx4 v[108:111], v[2:3], off offset:32
	global_load_dwordx4 v[112:115], v[0:1], off offset:64
	global_load_dwordx4 v[116:119], v[0:1], off offset:96
	global_load_dwordx4 v[120:123], v[2:3], off offset:64
	global_load_dwordx4 v[124:127], v[2:3], off offset:96
	v_sub_u32_e64 v0, s17, 4 clamp
	s_or_b32 s14, s4, s33
	v_readfirstlane_b32 s4, v0
	s_min_u32 s20, s4, 56
	s_lshl_b32 s4, s14, 3
	s_ashr_i32 s5, s4, 31
	s_lshl_b32 s1, s33, 6
	s_lshl_b64 s[4:5], s[4:5], 12
	s_add_u32 s4, s41, s4
	s_addc_u32 s5, s42, s5
	s_ashr_i32 s15, s14, 31
	s_lshl_b64 s[14:15], s[14:15], 19
	s_lshl_b32 s29, s20, 13
	s_or_b32 s14, s14, s29
	s_add_u32 s33, s18, s14
	s_addc_u32 s34, s19, s15
	s_add_u32 s35, s43, s14
	s_addc_u32 s36, s44, s15
	s_lshl_b32 s14, s28, 7
	s_or_b32 s14, s14, s16
	s_ashr_i32 s15, s14, 31
	s_sub_i32 s37, s20, s17
	s_lshl_b64 s[14:15], s[14:15], 12
	v_xor_b32_e32 v48, 0x80000000, v183
	s_add_u32 s14, s45, s14
	v_mov_b32_e32 v185, 0
	v_ashrrev_i32_e32 v173, 31, v172
	s_mov_b32 s2, 0
	v_mov_b32_e32 v49, v48
	v_mov_b32_e32 v50, v48
	v_mov_b32_e32 v51, v48
	v_mov_b32_e32 v52, v48
	v_mov_b32_e32 v53, v48
	v_mov_b32_e32 v54, v48
	v_mov_b32_e32 v55, v48
	v_mov_b32_e32 v56, v48
	v_mov_b32_e32 v57, v48
	v_mov_b32_e32 v58, v48
	v_mov_b32_e32 v59, v48
	v_mov_b32_e32 v60, v48
	v_mov_b32_e32 v61, v48
	v_mov_b32_e32 v62, v48
	v_mov_b32_e32 v63, v48
	s_addc_u32 s15, s46, s15
	s_mov_b32 s16, -8
	s_mov_b32 s39, 0
	v_mov_b32_e32 v184, 0
	v_mov_b32_e32 v32, 0
	v_mov_b32_e32 v33, v185
	v_mov_b32_e32 v34, v185
	v_mov_b32_e32 v35, v185
	v_mov_b32_e32 v36, v185
	v_mov_b32_e32 v37, v185
	v_mov_b32_e32 v38, v185
	v_mov_b32_e32 v39, v185
	v_mov_b32_e32 v40, v185
	v_mov_b32_e32 v41, v185
	v_mov_b32_e32 v42, v185
	v_mov_b32_e32 v43, v185
	v_mov_b32_e32 v44, v185
	v_mov_b32_e32 v45, v185
	v_mov_b32_e32 v46, v185
	v_mov_b32_e32 v47, v185
	v_mov_b32_e32 v64, 0
	v_mov_b32_e32 v65, v185
	v_mov_b32_e32 v66, v185
	v_mov_b32_e32 v67, v185
	v_mov_b32_e32 v68, v185
	v_mov_b32_e32 v69, v185
	v_mov_b32_e32 v70, v185
	v_mov_b32_e32 v71, v185
	v_mov_b32_e32 v72, v185
	v_mov_b32_e32 v73, v185
	v_mov_b32_e32 v74, v185
	v_mov_b32_e32 v75, v185
	v_mov_b32_e32 v76, v185
	v_mov_b32_e32 v77, v185
	v_mov_b32_e32 v78, v185
	v_mov_b32_e32 v79, v185
	v_mov_b32_e32 v16, 0
	v_mov_b32_e32 v17, v185
	v_mov_b32_e32 v18, v185
	v_mov_b32_e32 v19, v185
	v_mov_b32_e32 v20, v185
	v_mov_b32_e32 v21, v185
	v_mov_b32_e32 v22, v185
	v_mov_b32_e32 v23, v185
	v_mov_b32_e32 v24, v185
	v_mov_b32_e32 v25, v185
	v_mov_b32_e32 v26, v185
	v_mov_b32_e32 v27, v185
	v_mov_b32_e32 v28, v185
	v_mov_b32_e32 v29, v185
	v_mov_b32_e32 v30, v185
	v_mov_b32_e32 v31, v185
	v_mov_b32_e32 v0, 0
	v_mov_b32_e32 v1, v185
	v_mov_b32_e32 v2, v185
	v_mov_b32_e32 v3, v185
	v_mov_b32_e32 v4, v185
	v_mov_b32_e32 v5, v185
	v_mov_b32_e32 v6, v185
	v_mov_b32_e32 v7, v185
	v_mov_b32_e32 v8, v185
	v_mov_b32_e32 v9, v185
	v_mov_b32_e32 v10, v185
	v_mov_b32_e32 v11, v185
	v_mov_b32_e32 v12, v185
	v_mov_b32_e32 v13, v185
	v_mov_b32_e32 v14, v185
	v_mov_b32_e32 v15, v185
	v_lshlrev_b32_e32 v168, 4, v160
	v_lshl_add_u32 v255, v178, 2, v161
	s_lshl_b32 s68, s37, 9
	s_add_i32 s68, s68, s40
	s_addk_i32 s68, 0xe7c
	v_add_u32_e32 v255, s68, v255
	v_add_u32_e32 v252, 0x13000, v168
	s_barrier
	s_lshl_b32 s68, s85, 12
	s_add_u32 s54, s4, s68
	s_addc_u32 s55, s5, 0
	s_add_u32 s56, s14, s68
	s_addc_u32 s57, s15, 0
	s_add_i32 m0, s68, 0x13000
	s_nop 0
	global_load_lds_dwordx4 v168, s[54:55]
	global_load_lds_dwordx4 v168, s[54:55] offset:1024
	global_load_lds_dwordx4 v168, s[54:55] offset:2048
	global_load_lds_dwordx4 v168, s[54:55] offset:3072
	s_add_i32 m0, s68, 0x1b000
	s_nop 0
	global_load_lds_dwordx4 v168, s[56:57]
	global_load_lds_dwordx4 v168, s[56:57] offset:1024
	global_load_lds_dwordx4 v168, s[56:57] offset:2048
	global_load_lds_dwordx4 v168, s[56:57] offset:3072
	s_waitcnt vmcnt(0)
	s_barrier
	ds_read_b128 v[136:139], v252 offset:0
	ds_read_b128 v[132:135], v252 offset:1024
	ds_read_b128 v[140:143], v252 offset:2048
	ds_read_b128 v[128:131], v252 offset:3072
	ds_read_b128 v[144:147], v252 offset:32768
	ds_read_b128 v[148:151], v252 offset:33792
	ds_read_b128 v[152:155], v252 offset:34816
	ds_read_b128 v[156:159], v252 offset:35840
	s_waitcnt lgkmcnt(4)
	v_mfma_f32_32x32x16_bf16 v[80:95], v[136:139], v[96:99], v[48:63]
	v_mfma_f32_32x32x16_bf16 v[216:231], v[136:139], v[104:107], v[48:63]
	v_mfma_f32_32x32x16_bf16 v[80:95], v[132:135], v[100:103], v[80:95]
	v_mfma_f32_32x32x16_bf16 v[216:231], v[132:135], v[108:111], v[216:231]
	v_mfma_f32_32x32x16_bf16 v[80:95], v[140:143], v[112:115], v[80:95]
	v_mfma_f32_32x32x16_bf16 v[216:231], v[140:143], v[120:123], v[216:231]
	v_mfma_f32_32x32x16_bf16 v[80:95], v[128:131], v[116:119], v[80:95]
	v_mfma_f32_32x32x16_bf16 v[216:231], v[128:131], v[124:127], v[216:231]
	ds_read_b128 v[136:139], v252 offset:4096
	ds_read_b128 v[132:135], v252 offset:5120
	ds_read_b128 v[140:143], v252 offset:6144
	ds_read_b128 v[128:131], v252 offset:7168
	ds_read_b128 v[232:235], v252 offset:36864
	ds_read_b128 v[236:239], v252 offset:37888
	ds_read_b128 v[240:243], v252 offset:38912
	ds_read_b128 v[244:247], v252 offset:39936
	s_nop 3
	v_exp_f32_e32 v80, v80
	v_exp_f32_e32 v81, v81
	v_exp_f32_e32 v82, v82
	v_exp_f32_e32 v83, v83
	v_exp_f32_e32 v84, v84
	v_exp_f32_e32 v85, v85
	v_exp_f32_e32 v86, v86
	v_exp_f32_e32 v87, v87
	v_exp_f32_e32 v88, v88
	v_exp_f32_e32 v89, v89
	v_exp_f32_e32 v90, v90
	v_exp_f32_e32 v91, v91
	v_exp_f32_e32 v92, v92
	v_exp_f32_e32 v93, v93
	v_exp_f32_e32 v94, v94
	v_exp_f32_e32 v95, v95
	v_pk_add_f32 v[186:187], v[80:81], v[82:83]
	v_pk_add_f32 v[188:189], v[84:85], v[86:87]
	v_pk_add_f32 v[190:191], v[88:89], v[90:91]
	v_pk_add_f32 v[192:193], v[92:93], v[94:95]
	v_pk_add_f32 v[186:187], v[186:187], v[188:189]
	v_pk_add_f32 v[190:191], v[190:191], v[192:193]
	v_pk_add_f32 v[186:187], v[186:187], v[190:191]
	v_add_f32_e32 v186, v186, v187
	v_add_f32_e32 v185, v185, v186
	v_cvt_pk_bf16_f32 v80, v80, v81
	v_cvt_pk_bf16_f32 v81, v82, v83
	v_cvt_pk_bf16_f32 v82, v84, v85
	v_cvt_pk_bf16_f32 v83, v86, v87
	v_cvt_pk_bf16_f32 v84, v88, v89
	v_cvt_pk_bf16_f32 v85, v90, v91
	v_cvt_pk_bf16_f32 v86, v92, v93
	v_cvt_pk_bf16_f32 v87, v94, v95
	s_waitcnt lgkmcnt(8)
	s_nop 0
	v_mfma_f32_32x32x16_bf16 v[64:79], v[144:147], v[80:83], v[64:79]
	v_mfma_f32_32x32x16_bf16 v[32:47], v[148:151], v[80:83], v[32:47]
	v_mfma_f32_32x32x16_bf16 v[64:79], v[152:155], v[84:87], v[64:79]
	v_mfma_f32_32x32x16_bf16 v[32:47], v[156:159], v[84:87], v[32:47]
	v_exp_f32_e32 v216, v216
	v_exp_f32_e32 v217, v217
	v_exp_f32_e32 v218, v218
	v_exp_f32_e32 v219, v219
	v_exp_f32_e32 v220, v220
	v_exp_f32_e32 v221, v221
	v_exp_f32_e32 v222, v222
	v_exp_f32_e32 v223, v223
	v_exp_f32_e32 v224, v224
	v_exp_f32_e32 v225, v225
	v_exp_f32_e32 v226, v226
	v_exp_f32_e32 v227, v227
	v_exp_f32_e32 v228, v228
	v_exp_f32_e32 v229, v229
	v_exp_f32_e32 v230, v230
	v_exp_f32_e32 v231, v231
	v_pk_add_f32 v[194:195], v[216:217], v[218:219]
	v_pk_add_f32 v[196:197], v[220:221], v[222:223]
	v_pk_add_f32 v[198:199], v[224:225], v[226:227]
	v_pk_add_f32 v[200:201], v[228:229], v[230:231]
	v_pk_add_f32 v[194:195], v[194:195], v[196:197]
	v_pk_add_f32 v[198:199], v[198:199], v[200:201]
	v_pk_add_f32 v[194:195], v[194:195], v[198:199]
	v_add_f32_e32 v194, v194, v195
	v_add_f32_e32 v184, v184, v194
	v_cvt_pk_bf16_f32 v216, v216, v217
	v_cvt_pk_bf16_f32 v217, v218, v219
	v_cvt_pk_bf16_f32 v218, v220, v221
	v_cvt_pk_bf16_f32 v219, v222, v223
	v_cvt_pk_bf16_f32 v220, v224, v225
	v_cvt_pk_bf16_f32 v221, v226, v227
	v_cvt_pk_bf16_f32 v222, v228, v229
	v_cvt_pk_bf16_f32 v223, v230, v231
	s_nop 1
	v_mfma_f32_32x32x16_bf16 v[16:31], v[144:147], v[216:219], v[16:31]
	v_mfma_f32_32x32x16_bf16 v[0:15], v[148:151], v[216:219], v[0:15]
	v_mfma_f32_32x32x16_bf16 v[16:31], v[152:155], v[220:223], v[16:31]
	v_mfma_f32_32x32x16_bf16 v[0:15], v[156:159], v[220:223], v[0:15]
	s_waitcnt lgkmcnt(4)
	v_mfma_f32_32x32x16_bf16 v[80:95], v[136:139], v[96:99], v[48:63]
	v_mfma_f32_32x32x16_bf16 v[216:231], v[136:139], v[104:107], v[48:63]
	v_mfma_f32_32x32x16_bf16 v[80:95], v[132:135], v[100:103], v[80:95]
	v_mfma_f32_32x32x16_bf16 v[216:231], v[132:135], v[108:111], v[216:231]
	v_mfma_f32_32x32x16_bf16 v[80:95], v[140:143], v[112:115], v[80:95]
	v_mfma_f32_32x32x16_bf16 v[216:231], v[140:143], v[120:123], v[216:231]
	v_mfma_f32_32x32x16_bf16 v[80:95], v[128:131], v[116:119], v[80:95]
	v_mfma_f32_32x32x16_bf16 v[216:231], v[128:131], v[124:127], v[216:231]
	ds_read_b128 v[136:139], v252 offset:8192
	ds_read_b128 v[132:135], v252 offset:9216
	ds_read_b128 v[140:143], v252 offset:10240
	ds_read_b128 v[128:131], v252 offset:11264
	ds_read_b128 v[144:147], v252 offset:40960
	ds_read_b128 v[148:151], v252 offset:41984
	ds_read_b128 v[152:155], v252 offset:43008
	ds_read_b128 v[156:159], v252 offset:44032
	s_nop 3
	v_exp_f32_e32 v80, v80
	v_exp_f32_e32 v81, v81
	v_exp_f32_e32 v82, v82
	v_exp_f32_e32 v83, v83
	v_exp_f32_e32 v84, v84
	v_exp_f32_e32 v85, v85
	v_exp_f32_e32 v86, v86
	v_exp_f32_e32 v87, v87
	v_exp_f32_e32 v88, v88
	v_exp_f32_e32 v89, v89
	v_exp_f32_e32 v90, v90
	v_exp_f32_e32 v91, v91
	v_exp_f32_e32 v92, v92
	v_exp_f32_e32 v93, v93
	v_exp_f32_e32 v94, v94
	v_exp_f32_e32 v95, v95
	v_pk_add_f32 v[186:187], v[80:81], v[82:83]
	v_pk_add_f32 v[188:189], v[84:85], v[86:87]
	v_pk_add_f32 v[190:191], v[88:89], v[90:91]
	v_pk_add_f32 v[192:193], v[92:93], v[94:95]
	v_pk_add_f32 v[186:187], v[186:187], v[188:189]
	v_pk_add_f32 v[190:191], v[190:191], v[192:193]
	v_pk_add_f32 v[186:187], v[186:187], v[190:191]
	v_add_f32_e32 v186, v186, v187
	v_add_f32_e32 v185, v185, v186
	v_cvt_pk_bf16_f32 v80, v80, v81
	v_cvt_pk_bf16_f32 v81, v82, v83
	v_cvt_pk_bf16_f32 v82, v84, v85
	v_cvt_pk_bf16_f32 v83, v86, v87
	v_cvt_pk_bf16_f32 v84, v88, v89
	v_cvt_pk_bf16_f32 v85, v90, v91
	v_cvt_pk_bf16_f32 v86, v92, v93
	v_cvt_pk_bf16_f32 v87, v94, v95
	s_waitcnt lgkmcnt(8)
	s_nop 0
	v_mfma_f32_32x32x16_bf16 v[64:79], v[232:235], v[80:83], v[64:79]
	v_mfma_f32_32x32x16_bf16 v[32:47], v[236:239], v[80:83], v[32:47]
	v_mfma_f32_32x32x16_bf16 v[64:79], v[240:243], v[84:87], v[64:79]
	v_mfma_f32_32x32x16_bf16 v[32:47], v[244:247], v[84:87], v[32:47]
	v_exp_f32_e32 v216, v216
	v_exp_f32_e32 v217, v217
	v_exp_f32_e32 v218, v218
	v_exp_f32_e32 v219, v219
	v_exp_f32_e32 v220, v220
	v_exp_f32_e32 v221, v221
	v_exp_f32_e32 v222, v222
	v_exp_f32_e32 v223, v223
	v_exp_f32_e32 v224, v224
	v_exp_f32_e32 v225, v225
	v_exp_f32_e32 v226, v226
	v_exp_f32_e32 v227, v227
	v_exp_f32_e32 v228, v228
	v_exp_f32_e32 v229, v229
	v_exp_f32_e32 v230, v230
	v_exp_f32_e32 v231, v231
	v_pk_add_f32 v[194:195], v[216:217], v[218:219]
	v_pk_add_f32 v[196:197], v[220:221], v[222:223]
	v_pk_add_f32 v[198:199], v[224:225], v[226:227]
	v_pk_add_f32 v[200:201], v[228:229], v[230:231]
	v_pk_add_f32 v[194:195], v[194:195], v[196:197]
	v_pk_add_f32 v[198:199], v[198:199], v[200:201]
	v_pk_add_f32 v[194:195], v[194:195], v[198:199]
	v_add_f32_e32 v194, v194, v195
	v_add_f32_e32 v184, v184, v194
	v_cvt_pk_bf16_f32 v216, v216, v217
	v_cvt_pk_bf16_f32 v217, v218, v219
	v_cvt_pk_bf16_f32 v218, v220, v221
	v_cvt_pk_bf16_f32 v219, v222, v223
	v_cvt_pk_bf16_f32 v220, v224, v225
	v_cvt_pk_bf16_f32 v221, v226, v227
	v_cvt_pk_bf16_f32 v222, v228, v229
	v_cvt_pk_bf16_f32 v223, v230, v231
	s_nop 1
	v_mfma_f32_32x32x16_bf16 v[16:31], v[232:235], v[216:219], v[16:31]
	v_mfma_f32_32x32x16_bf16 v[0:15], v[236:239], v[216:219], v[0:15]
	v_mfma_f32_32x32x16_bf16 v[16:31], v[240:243], v[220:223], v[16:31]
	v_mfma_f32_32x32x16_bf16 v[0:15], v[244:247], v[220:223], v[0:15]
	s_waitcnt lgkmcnt(4)
	v_mfma_f32_32x32x16_bf16 v[80:95], v[136:139], v[96:99], v[48:63]
	v_mfma_f32_32x32x16_bf16 v[216:231], v[136:139], v[104:107], v[48:63]
	v_mfma_f32_32x32x16_bf16 v[80:95], v[132:135], v[100:103], v[80:95]
	v_mfma_f32_32x32x16_bf16 v[216:231], v[132:135], v[108:111], v[216:231]
	v_mfma_f32_32x32x16_bf16 v[80:95], v[140:143], v[112:115], v[80:95]
	v_mfma_f32_32x32x16_bf16 v[216:231], v[140:143], v[120:123], v[216:231]
	v_mfma_f32_32x32x16_bf16 v[80:95], v[128:131], v[116:119], v[80:95]
	v_mfma_f32_32x32x16_bf16 v[216:231], v[128:131], v[124:127], v[216:231]
	ds_read_b128 v[136:139], v252 offset:12288
	ds_read_b128 v[132:135], v252 offset:13312
	ds_read_b128 v[140:143], v252 offset:14336
	ds_read_b128 v[128:131], v252 offset:15360
	ds_read_b128 v[232:235], v252 offset:45056
	ds_read_b128 v[236:239], v252 offset:46080
	ds_read_b128 v[240:243], v252 offset:47104
	ds_read_b128 v[244:247], v252 offset:48128
	s_nop 3
	v_exp_f32_e32 v80, v80
	v_exp_f32_e32 v81, v81
	v_exp_f32_e32 v82, v82
	v_exp_f32_e32 v83, v83
	v_exp_f32_e32 v84, v84
	v_exp_f32_e32 v85, v85
	v_exp_f32_e32 v86, v86
	v_exp_f32_e32 v87, v87
	v_exp_f32_e32 v88, v88
	v_exp_f32_e32 v89, v89
	v_exp_f32_e32 v90, v90
	v_exp_f32_e32 v91, v91
	v_exp_f32_e32 v92, v92
	v_exp_f32_e32 v93, v93
	v_exp_f32_e32 v94, v94
	v_exp_f32_e32 v95, v95
	v_pk_add_f32 v[186:187], v[80:81], v[82:83]
	v_pk_add_f32 v[188:189], v[84:85], v[86:87]
	v_pk_add_f32 v[190:191], v[88:89], v[90:91]
	v_pk_add_f32 v[192:193], v[92:93], v[94:95]
	v_pk_add_f32 v[186:187], v[186:187], v[188:189]
	v_pk_add_f32 v[190:191], v[190:191], v[192:193]
	v_pk_add_f32 v[186:187], v[186:187], v[190:191]
	v_add_f32_e32 v186, v186, v187
	v_add_f32_e32 v185, v185, v186
	v_cvt_pk_bf16_f32 v80, v80, v81
	v_cvt_pk_bf16_f32 v81, v82, v83
	v_cvt_pk_bf16_f32 v82, v84, v85
	v_cvt_pk_bf16_f32 v83, v86, v87
	v_cvt_pk_bf16_f32 v84, v88, v89
	v_cvt_pk_bf16_f32 v85, v90, v91
	v_cvt_pk_bf16_f32 v86, v92, v93
	v_cvt_pk_bf16_f32 v87, v94, v95
	s_waitcnt lgkmcnt(8)
	s_nop 0
	v_mfma_f32_32x32x16_bf16 v[64:79], v[144:147], v[80:83], v[64:79]
	v_mfma_f32_32x32x16_bf16 v[32:47], v[148:151], v[80:83], v[32:47]
	v_mfma_f32_32x32x16_bf16 v[64:79], v[152:155], v[84:87], v[64:79]
	v_mfma_f32_32x32x16_bf16 v[32:47], v[156:159], v[84:87], v[32:47]
	v_exp_f32_e32 v216, v216
	v_exp_f32_e32 v217, v217
	v_exp_f32_e32 v218, v218
	v_exp_f32_e32 v219, v219
	v_exp_f32_e32 v220, v220
	v_exp_f32_e32 v221, v221
	v_exp_f32_e32 v222, v222
	v_exp_f32_e32 v223, v223
	v_exp_f32_e32 v224, v224
	v_exp_f32_e32 v225, v225
	v_exp_f32_e32 v226, v226
	v_exp_f32_e32 v227, v227
	v_exp_f32_e32 v228, v228
	v_exp_f32_e32 v229, v229
	v_exp_f32_e32 v230, v230
	v_exp_f32_e32 v231, v231
	v_pk_add_f32 v[194:195], v[216:217], v[218:219]
	v_pk_add_f32 v[196:197], v[220:221], v[222:223]
	v_pk_add_f32 v[198:199], v[224:225], v[226:227]
	v_pk_add_f32 v[200:201], v[228:229], v[230:231]
	v_pk_add_f32 v[194:195], v[194:195], v[196:197]
	v_pk_add_f32 v[198:199], v[198:199], v[200:201]
	v_pk_add_f32 v[194:195], v[194:195], v[198:199]
	v_add_f32_e32 v194, v194, v195
	v_add_f32_e32 v184, v184, v194
	v_cvt_pk_bf16_f32 v216, v216, v217
	v_cvt_pk_bf16_f32 v217, v218, v219
	v_cvt_pk_bf16_f32 v218, v220, v221
	v_cvt_pk_bf16_f32 v219, v222, v223
	v_cvt_pk_bf16_f32 v220, v224, v225
	v_cvt_pk_bf16_f32 v221, v226, v227
	v_cvt_pk_bf16_f32 v222, v228, v229
	v_cvt_pk_bf16_f32 v223, v230, v231
	s_nop 1
	v_mfma_f32_32x32x16_bf16 v[16:31], v[144:147], v[216:219], v[16:31]
	v_mfma_f32_32x32x16_bf16 v[0:15], v[148:151], v[216:219], v[0:15]
	v_mfma_f32_32x32x16_bf16 v[16:31], v[152:155], v[220:223], v[16:31]
	v_mfma_f32_32x32x16_bf16 v[0:15], v[156:159], v[220:223], v[0:15]
	s_waitcnt lgkmcnt(4)
	v_mfma_f32_32x32x16_bf16 v[80:95], v[136:139], v[96:99], v[48:63]
	v_mfma_f32_32x32x16_bf16 v[216:231], v[136:139], v[104:107], v[48:63]
	v_mfma_f32_32x32x16_bf16 v[80:95], v[132:135], v[100:103], v[80:95]
	v_mfma_f32_32x32x16_bf16 v[216:231], v[132:135], v[108:111], v[216:231]
	v_mfma_f32_32x32x16_bf16 v[80:95], v[140:143], v[112:115], v[80:95]
	v_mfma_f32_32x32x16_bf16 v[216:231], v[140:143], v[120:123], v[216:231]
	v_mfma_f32_32x32x16_bf16 v[80:95], v[128:131], v[116:119], v[80:95]
	v_mfma_f32_32x32x16_bf16 v[216:231], v[128:131], v[124:127], v[216:231]
	ds_read_b128 v[136:139], v252 offset:16384
	ds_read_b128 v[132:135], v252 offset:17408
	ds_read_b128 v[140:143], v252 offset:18432
	ds_read_b128 v[128:131], v252 offset:19456
	ds_read_b128 v[144:147], v252 offset:49152
	ds_read_b128 v[148:151], v252 offset:50176
	ds_read_b128 v[152:155], v252 offset:51200
	ds_read_b128 v[156:159], v252 offset:52224
	s_nop 3
	v_exp_f32_e32 v80, v80
	v_exp_f32_e32 v81, v81
	v_exp_f32_e32 v82, v82
	v_exp_f32_e32 v83, v83
	v_exp_f32_e32 v84, v84
	v_exp_f32_e32 v85, v85
	v_exp_f32_e32 v86, v86
	v_exp_f32_e32 v87, v87
	v_exp_f32_e32 v88, v88
	v_exp_f32_e32 v89, v89
	v_exp_f32_e32 v90, v90
	v_exp_f32_e32 v91, v91
	v_exp_f32_e32 v92, v92
	v_exp_f32_e32 v93, v93
	v_exp_f32_e32 v94, v94
	v_exp_f32_e32 v95, v95
	v_pk_add_f32 v[186:187], v[80:81], v[82:83]
	v_pk_add_f32 v[188:189], v[84:85], v[86:87]
	v_pk_add_f32 v[190:191], v[88:89], v[90:91]
	v_pk_add_f32 v[192:193], v[92:93], v[94:95]
	v_pk_add_f32 v[186:187], v[186:187], v[188:189]
	v_pk_add_f32 v[190:191], v[190:191], v[192:193]
	v_pk_add_f32 v[186:187], v[186:187], v[190:191]
	v_add_f32_e32 v186, v186, v187
	v_add_f32_e32 v185, v185, v186
	v_cvt_pk_bf16_f32 v80, v80, v81
	v_cvt_pk_bf16_f32 v81, v82, v83
	v_cvt_pk_bf16_f32 v82, v84, v85
	v_cvt_pk_bf16_f32 v83, v86, v87
	v_cvt_pk_bf16_f32 v84, v88, v89
	v_cvt_pk_bf16_f32 v85, v90, v91
	v_cvt_pk_bf16_f32 v86, v92, v93
	v_cvt_pk_bf16_f32 v87, v94, v95
	s_waitcnt lgkmcnt(8)
	s_nop 0
	v_mfma_f32_32x32x16_bf16 v[64:79], v[232:235], v[80:83], v[64:79]
	v_mfma_f32_32x32x16_bf16 v[32:47], v[236:239], v[80:83], v[32:47]
	v_mfma_f32_32x32x16_bf16 v[64:79], v[240:243], v[84:87], v[64:79]
	v_mfma_f32_32x32x16_bf16 v[32:47], v[244:247], v[84:87], v[32:47]
	v_exp_f32_e32 v216, v216
	v_exp_f32_e32 v217, v217
	v_exp_f32_e32 v218, v218
	v_exp_f32_e32 v219, v219
	v_exp_f32_e32 v220, v220
	v_exp_f32_e32 v221, v221
	v_exp_f32_e32 v222, v222
	v_exp_f32_e32 v223, v223
	v_exp_f32_e32 v224, v224
	v_exp_f32_e32 v225, v225
	v_exp_f32_e32 v226, v226
	v_exp_f32_e32 v227, v227
	v_exp_f32_e32 v228, v228
	v_exp_f32_e32 v229, v229
	v_exp_f32_e32 v230, v230
	v_exp_f32_e32 v231, v231
	v_pk_add_f32 v[194:195], v[216:217], v[218:219]
	v_pk_add_f32 v[196:197], v[220:221], v[222:223]
	v_pk_add_f32 v[198:199], v[224:225], v[226:227]
	v_pk_add_f32 v[200:201], v[228:229], v[230:231]
	v_pk_add_f32 v[194:195], v[194:195], v[196:197]
	v_pk_add_f32 v[198:199], v[198:199], v[200:201]
	v_pk_add_f32 v[194:195], v[194:195], v[198:199]
	v_add_f32_e32 v194, v194, v195
	v_add_f32_e32 v184, v184, v194
	v_cvt_pk_bf16_f32 v216, v216, v217
	v_cvt_pk_bf16_f32 v217, v218, v219
	v_cvt_pk_bf16_f32 v218, v220, v221
	v_cvt_pk_bf16_f32 v219, v222, v223
	v_cvt_pk_bf16_f32 v220, v224, v225
	v_cvt_pk_bf16_f32 v221, v226, v227
	v_cvt_pk_bf16_f32 v222, v228, v229
	v_cvt_pk_bf16_f32 v223, v230, v231
	s_nop 1
	v_mfma_f32_32x32x16_bf16 v[16:31], v[232:235], v[216:219], v[16:31]
	v_mfma_f32_32x32x16_bf16 v[0:15], v[236:239], v[216:219], v[0:15]
	v_mfma_f32_32x32x16_bf16 v[16:31], v[240:243], v[220:223], v[16:31]
	v_mfma_f32_32x32x16_bf16 v[0:15], v[244:247], v[220:223], v[0:15]
	s_waitcnt lgkmcnt(4)
	v_mfma_f32_32x32x16_bf16 v[80:95], v[136:139], v[96:99], v[48:63]
	v_mfma_f32_32x32x16_bf16 v[216:231], v[136:139], v[104:107], v[48:63]
	v_mfma_f32_32x32x16_bf16 v[80:95], v[132:135], v[100:103], v[80:95]
	v_mfma_f32_32x32x16_bf16 v[216:231], v[132:135], v[108:111], v[216:231]
	v_mfma_f32_32x32x16_bf16 v[80:95], v[140:143], v[112:115], v[80:95]
	v_mfma_f32_32x32x16_bf16 v[216:231], v[140:143], v[120:123], v[216:231]
	v_mfma_f32_32x32x16_bf16 v[80:95], v[128:131], v[116:119], v[80:95]
	v_mfma_f32_32x32x16_bf16 v[216:231], v[128:131], v[124:127], v[216:231]
	ds_read_b128 v[136:139], v252 offset:20480
	ds_read_b128 v[132:135], v252 offset:21504
	ds_read_b128 v[140:143], v252 offset:22528
	ds_read_b128 v[128:131], v252 offset:23552
	ds_read_b128 v[232:235], v252 offset:53248
	ds_read_b128 v[236:239], v252 offset:54272
	ds_read_b128 v[240:243], v252 offset:55296
	ds_read_b128 v[244:247], v252 offset:56320
	s_nop 3
	v_exp_f32_e32 v80, v80
	v_exp_f32_e32 v81, v81
	v_exp_f32_e32 v82, v82
	v_exp_f32_e32 v83, v83
	v_exp_f32_e32 v84, v84
	v_exp_f32_e32 v85, v85
	v_exp_f32_e32 v86, v86
	v_exp_f32_e32 v87, v87
	v_exp_f32_e32 v88, v88
	v_exp_f32_e32 v89, v89
	v_exp_f32_e32 v90, v90
	v_exp_f32_e32 v91, v91
	v_exp_f32_e32 v92, v92
	v_exp_f32_e32 v93, v93
	v_exp_f32_e32 v94, v94
	v_exp_f32_e32 v95, v95
	v_pk_add_f32 v[186:187], v[80:81], v[82:83]
	v_pk_add_f32 v[188:189], v[84:85], v[86:87]
	v_pk_add_f32 v[190:191], v[88:89], v[90:91]
	v_pk_add_f32 v[192:193], v[92:93], v[94:95]
	v_pk_add_f32 v[186:187], v[186:187], v[188:189]
	v_pk_add_f32 v[190:191], v[190:191], v[192:193]
	v_pk_add_f32 v[186:187], v[186:187], v[190:191]
	v_add_f32_e32 v186, v186, v187
	v_add_f32_e32 v185, v185, v186
	v_cvt_pk_bf16_f32 v80, v80, v81
	v_cvt_pk_bf16_f32 v81, v82, v83
	v_cvt_pk_bf16_f32 v82, v84, v85
	v_cvt_pk_bf16_f32 v83, v86, v87
	v_cvt_pk_bf16_f32 v84, v88, v89
	v_cvt_pk_bf16_f32 v85, v90, v91
	v_cvt_pk_bf16_f32 v86, v92, v93
	v_cvt_pk_bf16_f32 v87, v94, v95
	s_waitcnt lgkmcnt(8)
	s_nop 0
	v_mfma_f32_32x32x16_bf16 v[64:79], v[144:147], v[80:83], v[64:79]
	v_mfma_f32_32x32x16_bf16 v[32:47], v[148:151], v[80:83], v[32:47]
	v_mfma_f32_32x32x16_bf16 v[64:79], v[152:155], v[84:87], v[64:79]
	v_mfma_f32_32x32x16_bf16 v[32:47], v[156:159], v[84:87], v[32:47]
	v_exp_f32_e32 v216, v216
	v_exp_f32_e32 v217, v217
	v_exp_f32_e32 v218, v218
	v_exp_f32_e32 v219, v219
	v_exp_f32_e32 v220, v220
	v_exp_f32_e32 v221, v221
	v_exp_f32_e32 v222, v222
	v_exp_f32_e32 v223, v223
	v_exp_f32_e32 v224, v224
	v_exp_f32_e32 v225, v225
	v_exp_f32_e32 v226, v226
	v_exp_f32_e32 v227, v227
	v_exp_f32_e32 v228, v228
	v_exp_f32_e32 v229, v229
	v_exp_f32_e32 v230, v230
	v_exp_f32_e32 v231, v231
	v_pk_add_f32 v[194:195], v[216:217], v[218:219]
	v_pk_add_f32 v[196:197], v[220:221], v[222:223]
	v_pk_add_f32 v[198:199], v[224:225], v[226:227]
	v_pk_add_f32 v[200:201], v[228:229], v[230:231]
	v_pk_add_f32 v[194:195], v[194:195], v[196:197]
	v_pk_add_f32 v[198:199], v[198:199], v[200:201]
	v_pk_add_f32 v[194:195], v[194:195], v[198:199]
	v_add_f32_e32 v194, v194, v195
	v_add_f32_e32 v184, v184, v194
	v_cvt_pk_bf16_f32 v216, v216, v217
	v_cvt_pk_bf16_f32 v217, v218, v219
	v_cvt_pk_bf16_f32 v218, v220, v221
	v_cvt_pk_bf16_f32 v219, v222, v223
	v_cvt_pk_bf16_f32 v220, v224, v225
	v_cvt_pk_bf16_f32 v221, v226, v227
	v_cvt_pk_bf16_f32 v222, v228, v229
	v_cvt_pk_bf16_f32 v223, v230, v231
	s_nop 1
	v_mfma_f32_32x32x16_bf16 v[16:31], v[144:147], v[216:219], v[16:31]
	v_mfma_f32_32x32x16_bf16 v[0:15], v[148:151], v[216:219], v[0:15]
	v_mfma_f32_32x32x16_bf16 v[16:31], v[152:155], v[220:223], v[16:31]
	v_mfma_f32_32x32x16_bf16 v[0:15], v[156:159], v[220:223], v[0:15]
	s_waitcnt lgkmcnt(4)
	v_mfma_f32_32x32x16_bf16 v[80:95], v[136:139], v[96:99], v[48:63]
	v_mfma_f32_32x32x16_bf16 v[216:231], v[136:139], v[104:107], v[48:63]
	v_mfma_f32_32x32x16_bf16 v[80:95], v[132:135], v[100:103], v[80:95]
	v_mfma_f32_32x32x16_bf16 v[216:231], v[132:135], v[108:111], v[216:231]
	v_mfma_f32_32x32x16_bf16 v[80:95], v[140:143], v[112:115], v[80:95]
	v_mfma_f32_32x32x16_bf16 v[216:231], v[140:143], v[120:123], v[216:231]
	v_mfma_f32_32x32x16_bf16 v[80:95], v[128:131], v[116:119], v[80:95]
	v_mfma_f32_32x32x16_bf16 v[216:231], v[128:131], v[124:127], v[216:231]
	ds_read_b128 v[136:139], v252 offset:24576
	ds_read_b128 v[132:135], v252 offset:25600
	ds_read_b128 v[140:143], v252 offset:26624
	ds_read_b128 v[128:131], v252 offset:27648
	ds_read_b128 v[144:147], v252 offset:57344
	ds_read_b128 v[148:151], v252 offset:58368
	ds_read_b128 v[152:155], v252 offset:59392
	ds_read_b128 v[156:159], v252 offset:60416
	s_nop 3
	v_exp_f32_e32 v80, v80
	v_exp_f32_e32 v81, v81
	v_exp_f32_e32 v82, v82
	v_exp_f32_e32 v83, v83
	v_exp_f32_e32 v84, v84
	v_exp_f32_e32 v85, v85
	v_exp_f32_e32 v86, v86
	v_exp_f32_e32 v87, v87
	v_exp_f32_e32 v88, v88
	v_exp_f32_e32 v89, v89
	v_exp_f32_e32 v90, v90
	v_exp_f32_e32 v91, v91
	v_exp_f32_e32 v92, v92
	v_exp_f32_e32 v93, v93
	v_exp_f32_e32 v94, v94
	v_exp_f32_e32 v95, v95
	v_pk_add_f32 v[186:187], v[80:81], v[82:83]
	v_pk_add_f32 v[188:189], v[84:85], v[86:87]
	v_pk_add_f32 v[190:191], v[88:89], v[90:91]
	v_pk_add_f32 v[192:193], v[92:93], v[94:95]
	v_pk_add_f32 v[186:187], v[186:187], v[188:189]
	v_pk_add_f32 v[190:191], v[190:191], v[192:193]
	v_pk_add_f32 v[186:187], v[186:187], v[190:191]
	v_add_f32_e32 v186, v186, v187
	v_add_f32_e32 v185, v185, v186
	v_cvt_pk_bf16_f32 v80, v80, v81
	v_cvt_pk_bf16_f32 v81, v82, v83
	v_cvt_pk_bf16_f32 v82, v84, v85
	v_cvt_pk_bf16_f32 v83, v86, v87
	v_cvt_pk_bf16_f32 v84, v88, v89
	v_cvt_pk_bf16_f32 v85, v90, v91
	v_cvt_pk_bf16_f32 v86, v92, v93
	v_cvt_pk_bf16_f32 v87, v94, v95
	s_waitcnt lgkmcnt(8)
	s_nop 0
	v_mfma_f32_32x32x16_bf16 v[64:79], v[232:235], v[80:83], v[64:79]
	v_mfma_f32_32x32x16_bf16 v[32:47], v[236:239], v[80:83], v[32:47]
	v_mfma_f32_32x32x16_bf16 v[64:79], v[240:243], v[84:87], v[64:79]
	v_mfma_f32_32x32x16_bf16 v[32:47], v[244:247], v[84:87], v[32:47]
	v_exp_f32_e32 v216, v216
	v_exp_f32_e32 v217, v217
	v_exp_f32_e32 v218, v218
	v_exp_f32_e32 v219, v219
	v_exp_f32_e32 v220, v220
	v_exp_f32_e32 v221, v221
	v_exp_f32_e32 v222, v222
	v_exp_f32_e32 v223, v223
	v_exp_f32_e32 v224, v224
	v_exp_f32_e32 v225, v225
	v_exp_f32_e32 v226, v226
	v_exp_f32_e32 v227, v227
	v_exp_f32_e32 v228, v228
	v_exp_f32_e32 v229, v229
	v_exp_f32_e32 v230, v230
	v_exp_f32_e32 v231, v231
	v_pk_add_f32 v[194:195], v[216:217], v[218:219]
	v_pk_add_f32 v[196:197], v[220:221], v[222:223]
	v_pk_add_f32 v[198:199], v[224:225], v[226:227]
	v_pk_add_f32 v[200:201], v[228:229], v[230:231]
	v_pk_add_f32 v[194:195], v[194:195], v[196:197]
	v_pk_add_f32 v[198:199], v[198:199], v[200:201]
	v_pk_add_f32 v[194:195], v[194:195], v[198:199]
	v_add_f32_e32 v194, v194, v195
	v_add_f32_e32 v184, v184, v194
	v_cvt_pk_bf16_f32 v216, v216, v217
	v_cvt_pk_bf16_f32 v217, v218, v219
	v_cvt_pk_bf16_f32 v218, v220, v221
	v_cvt_pk_bf16_f32 v219, v222, v223
	v_cvt_pk_bf16_f32 v220, v224, v225
	v_cvt_pk_bf16_f32 v221, v226, v227
	v_cvt_pk_bf16_f32 v222, v228, v229
	v_cvt_pk_bf16_f32 v223, v230, v231
	s_nop 1
	v_mfma_f32_32x32x16_bf16 v[16:31], v[232:235], v[216:219], v[16:31]
	v_mfma_f32_32x32x16_bf16 v[0:15], v[236:239], v[216:219], v[0:15]
	v_mfma_f32_32x32x16_bf16 v[16:31], v[240:243], v[220:223], v[16:31]
	v_mfma_f32_32x32x16_bf16 v[0:15], v[244:247], v[220:223], v[0:15]
	s_waitcnt lgkmcnt(4)
	v_mfma_f32_32x32x16_bf16 v[80:95], v[136:139], v[96:99], v[48:63]
	v_mfma_f32_32x32x16_bf16 v[216:231], v[136:139], v[104:107], v[48:63]
	v_mfma_f32_32x32x16_bf16 v[80:95], v[132:135], v[100:103], v[80:95]
	v_mfma_f32_32x32x16_bf16 v[216:231], v[132:135], v[108:111], v[216:231]
	v_mfma_f32_32x32x16_bf16 v[80:95], v[140:143], v[112:115], v[80:95]
	v_mfma_f32_32x32x16_bf16 v[216:231], v[140:143], v[120:123], v[216:231]
	v_mfma_f32_32x32x16_bf16 v[80:95], v[128:131], v[116:119], v[80:95]
	v_mfma_f32_32x32x16_bf16 v[216:231], v[128:131], v[124:127], v[216:231]
	ds_read_b128 v[136:139], v252 offset:28672
	ds_read_b128 v[132:135], v252 offset:29696
	ds_read_b128 v[140:143], v252 offset:30720
	ds_read_b128 v[128:131], v252 offset:31744
	ds_read_b128 v[232:235], v252 offset:61440
	ds_read_b128 v[236:239], v252 offset:62464
	ds_read_b128 v[240:243], v252 offset:63488
	ds_read_b128 v[244:247], v252 offset:64512
	s_nop 3
	v_exp_f32_e32 v80, v80
	v_exp_f32_e32 v81, v81
	v_exp_f32_e32 v82, v82
	v_exp_f32_e32 v83, v83
	v_exp_f32_e32 v84, v84
	v_exp_f32_e32 v85, v85
	v_exp_f32_e32 v86, v86
	v_exp_f32_e32 v87, v87
	v_exp_f32_e32 v88, v88
	v_exp_f32_e32 v89, v89
	v_exp_f32_e32 v90, v90
	v_exp_f32_e32 v91, v91
	v_exp_f32_e32 v92, v92
	v_exp_f32_e32 v93, v93
	v_exp_f32_e32 v94, v94
	v_exp_f32_e32 v95, v95
	v_pk_add_f32 v[186:187], v[80:81], v[82:83]
	v_pk_add_f32 v[188:189], v[84:85], v[86:87]
	v_pk_add_f32 v[190:191], v[88:89], v[90:91]
	v_pk_add_f32 v[192:193], v[92:93], v[94:95]
	v_pk_add_f32 v[186:187], v[186:187], v[188:189]
	v_pk_add_f32 v[190:191], v[190:191], v[192:193]
	v_pk_add_f32 v[186:187], v[186:187], v[190:191]
	v_add_f32_e32 v186, v186, v187
	v_add_f32_e32 v185, v185, v186
	v_cvt_pk_bf16_f32 v80, v80, v81
	v_cvt_pk_bf16_f32 v81, v82, v83
	v_cvt_pk_bf16_f32 v82, v84, v85
	v_cvt_pk_bf16_f32 v83, v86, v87
	v_cvt_pk_bf16_f32 v84, v88, v89
	v_cvt_pk_bf16_f32 v85, v90, v91
	v_cvt_pk_bf16_f32 v86, v92, v93
	v_cvt_pk_bf16_f32 v87, v94, v95
	s_waitcnt lgkmcnt(8)
	s_nop 0
	v_mfma_f32_32x32x16_bf16 v[64:79], v[144:147], v[80:83], v[64:79]
	v_mfma_f32_32x32x16_bf16 v[32:47], v[148:151], v[80:83], v[32:47]
	v_mfma_f32_32x32x16_bf16 v[64:79], v[152:155], v[84:87], v[64:79]
	v_mfma_f32_32x32x16_bf16 v[32:47], v[156:159], v[84:87], v[32:47]
	v_exp_f32_e32 v216, v216
	v_exp_f32_e32 v217, v217
	v_exp_f32_e32 v218, v218
	v_exp_f32_e32 v219, v219
	v_exp_f32_e32 v220, v220
	v_exp_f32_e32 v221, v221
	v_exp_f32_e32 v222, v222
	v_exp_f32_e32 v223, v223
	v_exp_f32_e32 v224, v224
	v_exp_f32_e32 v225, v225
	v_exp_f32_e32 v226, v226
	v_exp_f32_e32 v227, v227
	v_exp_f32_e32 v228, v228
	v_exp_f32_e32 v229, v229
	v_exp_f32_e32 v230, v230
	v_exp_f32_e32 v231, v231
	v_pk_add_f32 v[194:195], v[216:217], v[218:219]
	v_pk_add_f32 v[196:197], v[220:221], v[222:223]
	v_pk_add_f32 v[198:199], v[224:225], v[226:227]
	v_pk_add_f32 v[200:201], v[228:229], v[230:231]
	v_pk_add_f32 v[194:195], v[194:195], v[196:197]
	v_pk_add_f32 v[198:199], v[198:199], v[200:201]
	v_pk_add_f32 v[194:195], v[194:195], v[198:199]
	v_add_f32_e32 v194, v194, v195
	v_add_f32_e32 v184, v184, v194
	v_cvt_pk_bf16_f32 v216, v216, v217
	v_cvt_pk_bf16_f32 v217, v218, v219
	v_cvt_pk_bf16_f32 v218, v220, v221
	v_cvt_pk_bf16_f32 v219, v222, v223
	v_cvt_pk_bf16_f32 v220, v224, v225
	v_cvt_pk_bf16_f32 v221, v226, v227
	v_cvt_pk_bf16_f32 v222, v228, v229
	v_cvt_pk_bf16_f32 v223, v230, v231
	s_nop 1
	v_mfma_f32_32x32x16_bf16 v[16:31], v[144:147], v[216:219], v[16:31]
	v_mfma_f32_32x32x16_bf16 v[0:15], v[148:151], v[216:219], v[0:15]
	v_mfma_f32_32x32x16_bf16 v[16:31], v[152:155], v[220:223], v[16:31]
	v_mfma_f32_32x32x16_bf16 v[0:15], v[156:159], v[220:223], v[0:15]
	s_waitcnt lgkmcnt(4)
	v_mfma_f32_32x32x16_bf16 v[80:95], v[136:139], v[96:99], v[48:63]
	v_mfma_f32_32x32x16_bf16 v[216:231], v[136:139], v[104:107], v[48:63]
	v_mfma_f32_32x32x16_bf16 v[80:95], v[132:135], v[100:103], v[80:95]
	v_mfma_f32_32x32x16_bf16 v[216:231], v[132:135], v[108:111], v[216:231]
	v_mfma_f32_32x32x16_bf16 v[80:95], v[140:143], v[112:115], v[80:95]
	v_mfma_f32_32x32x16_bf16 v[216:231], v[140:143], v[120:123], v[216:231]
	v_mfma_f32_32x32x16_bf16 v[80:95], v[128:131], v[116:119], v[80:95]
	v_mfma_f32_32x32x16_bf16 v[216:231], v[128:131], v[124:127], v[216:231]
	s_mov_b32 s54, s33
	s_mov_b32 s55, s34
	s_mov_b32 s56, s35
	s_mov_b32 s57, s36
	global_load_dwordx4 v[136:139], v168, s[54:55]
	global_load_dwordx4 v[132:135], v168, s[54:55] offset:1024
	global_load_dwordx4 v[140:143], v168, s[54:55] offset:2048
	global_load_dwordx4 v[128:131], v168, s[54:55] offset:3072
	global_load_dwordx4 v[144:147], v168, s[56:57]
	global_load_dwordx4 v[148:151], v168, s[56:57] offset:1024
	global_load_dwordx4 v[152:155], v168, s[56:57] offset:2048
	global_load_dwordx4 v[156:159], v168, s[56:57] offset:3072
	s_add_u32 s54, s54, 0x1000
	s_addc_u32 s55, s55, 0
	s_add_u32 s56, s56, 0x1000
	s_addc_u32 s57, s57, 0
	v_exp_f32_e32 v80, v80
	v_exp_f32_e32 v81, v81
	v_exp_f32_e32 v82, v82
	v_exp_f32_e32 v83, v83
	v_exp_f32_e32 v84, v84
	v_exp_f32_e32 v85, v85
	v_exp_f32_e32 v86, v86
	v_exp_f32_e32 v87, v87
	v_exp_f32_e32 v88, v88
	v_exp_f32_e32 v89, v89
	v_exp_f32_e32 v90, v90
	v_exp_f32_e32 v91, v91
	v_exp_f32_e32 v92, v92
	v_exp_f32_e32 v93, v93
	v_exp_f32_e32 v94, v94
	v_exp_f32_e32 v95, v95
	v_pk_add_f32 v[186:187], v[80:81], v[82:83]
	v_pk_add_f32 v[188:189], v[84:85], v[86:87]
	v_pk_add_f32 v[190:191], v[88:89], v[90:91]
	v_pk_add_f32 v[192:193], v[92:93], v[94:95]
	v_pk_add_f32 v[186:187], v[186:187], v[188:189]
	v_pk_add_f32 v[190:191], v[190:191], v[192:193]
	v_pk_add_f32 v[186:187], v[186:187], v[190:191]
	v_add_f32_e32 v186, v186, v187
	v_add_f32_e32 v185, v185, v186
	v_cvt_pk_bf16_f32 v80, v80, v81
	v_cvt_pk_bf16_f32 v81, v82, v83
	v_cvt_pk_bf16_f32 v82, v84, v85
	v_cvt_pk_bf16_f32 v83, v86, v87
	v_cvt_pk_bf16_f32 v84, v88, v89
	v_cvt_pk_bf16_f32 v85, v90, v91
	v_cvt_pk_bf16_f32 v86, v92, v93
	v_cvt_pk_bf16_f32 v87, v94, v95
	s_waitcnt lgkmcnt(0)
	s_nop 0
	v_mfma_f32_32x32x16_bf16 v[64:79], v[232:235], v[80:83], v[64:79]
	v_mfma_f32_32x32x16_bf16 v[32:47], v[236:239], v[80:83], v[32:47]
	v_mfma_f32_32x32x16_bf16 v[64:79], v[240:243], v[84:87], v[64:79]
	v_mfma_f32_32x32x16_bf16 v[32:47], v[244:247], v[84:87], v[32:47]
	v_exp_f32_e32 v216, v216
	v_exp_f32_e32 v217, v217
	v_exp_f32_e32 v218, v218
	v_exp_f32_e32 v219, v219
	v_exp_f32_e32 v220, v220
	v_exp_f32_e32 v221, v221
	v_exp_f32_e32 v222, v222
	v_exp_f32_e32 v223, v223
	v_exp_f32_e32 v224, v224
	v_exp_f32_e32 v225, v225
	v_exp_f32_e32 v226, v226
	v_exp_f32_e32 v227, v227
	v_exp_f32_e32 v228, v228
	v_exp_f32_e32 v229, v229
	v_exp_f32_e32 v230, v230
	v_exp_f32_e32 v231, v231
	v_pk_add_f32 v[194:195], v[216:217], v[218:219]
	v_pk_add_f32 v[196:197], v[220:221], v[222:223]
	v_pk_add_f32 v[198:199], v[224:225], v[226:227]
	v_pk_add_f32 v[200:201], v[228:229], v[230:231]
	v_pk_add_f32 v[194:195], v[194:195], v[196:197]
	v_pk_add_f32 v[198:199], v[198:199], v[200:201]
	v_pk_add_f32 v[194:195], v[194:195], v[198:199]
	v_add_f32_e32 v194, v194, v195
	v_add_f32_e32 v184, v184, v194
	v_cvt_pk_bf16_f32 v216, v216, v217
	v_cvt_pk_bf16_f32 v217, v218, v219
	v_cvt_pk_bf16_f32 v218, v220, v221
	v_cvt_pk_bf16_f32 v219, v222, v223
	v_cvt_pk_bf16_f32 v220, v224, v225
	v_cvt_pk_bf16_f32 v221, v226, v227
	v_cvt_pk_bf16_f32 v222, v228, v229
	v_cvt_pk_bf16_f32 v223, v230, v231
	s_nop 1
	v_mfma_f32_32x32x16_bf16 v[16:31], v[232:235], v[216:219], v[16:31]
	v_mfma_f32_32x32x16_bf16 v[0:15], v[236:239], v[216:219], v[0:15]
	v_mfma_f32_32x32x16_bf16 v[16:31], v[240:243], v[220:223], v[16:31]
	v_mfma_f32_32x32x16_bf16 v[0:15], v[244:247], v[220:223], v[0:15]
	s_mov_b32 s53, 0
.Lao_win_loop:
	ds_read2_b32 v[186:187], v255 offset0:32 offset1:33
	ds_read2_b32 v[188:189], v255 offset0:34 offset1:35
	ds_read2_b32 v[190:191], v255 offset0:40 offset1:41
	ds_read2_b32 v[192:193], v255 offset0:42 offset1:43
	ds_read2_b32 v[194:195], v255 offset0:48 offset1:49
	ds_read2_b32 v[196:197], v255 offset0:50 offset1:51
	ds_read2_b32 v[198:199], v255 offset0:56 offset1:57
	ds_read2_b32 v[200:201], v255 offset0:58 offset1:59
	ds_read_b128 v[204:207], v168 offset:0
	ds_read_b128 v[208:211], v168 offset:1024
	ds_read_b128 v[212:215], v168 offset:2048
	ds_read_b128 v[248:251], v168 offset:3072
	ds_read2_b32 v[202:203], v255 offset0:24 offset1:25
	ds_read2_b32 v[252:253], v255 offset0:26 offset1:27
	s_waitcnt vmcnt(4)
	v_mfma_f32_32x32x16_bf16 v[80:95], v[136:139], v[96:99], v[48:63]
	v_mfma_f32_32x32x16_bf16 v[216:231], v[136:139], v[104:107], v[48:63]
	v_mfma_f32_32x32x16_bf16 v[80:95], v[132:135], v[100:103], v[80:95]
	v_mfma_f32_32x32x16_bf16 v[216:231], v[132:135], v[108:111], v[216:231]
	v_mfma_f32_32x32x16_bf16 v[80:95], v[140:143], v[112:115], v[80:95]
	v_mfma_f32_32x32x16_bf16 v[216:231], v[140:143], v[120:123], v[216:231]
	v_mfma_f32_32x32x16_bf16 v[80:95], v[128:131], v[116:119], v[80:95]
	v_mfma_f32_32x32x16_bf16 v[216:231], v[128:131], v[124:127], v[216:231]
	global_load_dwordx4 v[136:139], v168, s[54:55]
	global_load_dwordx4 v[132:135], v168, s[54:55] offset:1024
	global_load_dwordx4 v[140:143], v168, s[54:55] offset:2048
	global_load_dwordx4 v[128:131], v168, s[54:55] offset:3072
	global_load_dwordx4 v[232:235], v168, s[56:57]
	global_load_dwordx4 v[236:239], v168, s[56:57] offset:1024
	global_load_dwordx4 v[240:243], v168, s[56:57] offset:2048
	global_load_dwordx4 v[244:247], v168, s[56:57] offset:3072
	s_add_u32 s54, s54, 0x1000
	s_addc_u32 s55, s55, 0
	s_add_u32 s56, s56, 0x1000
	s_addc_u32 s57, s57, 0
	s_waitcnt lgkmcnt(2)
	v_pk_add_f32 v[80:81], v[80:81], v[186:187]
	v_pk_add_f32 v[82:83], v[82:83], v[188:189]
	v_pk_add_f32 v[84:85], v[84:85], v[190:191]
	v_pk_add_f32 v[86:87], v[86:87], v[192:193]
	v_pk_add_f32 v[88:89], v[88:89], v[194:195]
	v_pk_add_f32 v[90:91], v[90:91], v[196:197]
	v_pk_add_f32 v[92:93], v[92:93], v[198:199]
	v_pk_add_f32 v[94:95], v[94:95], v[200:201]
	v_pk_add_f32 v[80:81], v[80:81], v[204:205]
	v_pk_add_f32 v[82:83], v[82:83], v[206:207]
	v_pk_add_f32 v[84:85], v[84:85], v[208:209]
	v_pk_add_f32 v[86:87], v[86:87], v[210:211]
	v_pk_add_f32 v[88:89], v[88:89], v[212:213]
	v_pk_add_f32 v[90:91], v[90:91], v[214:215]
	v_pk_add_f32 v[92:93], v[92:93], v[248:249]
	v_pk_add_f32 v[94:95], v[94:95], v[250:251]
	v_exp_f32_e32 v80, v80
	v_exp_f32_e32 v81, v81
	v_exp_f32_e32 v82, v82
	v_exp_f32_e32 v83, v83
	v_exp_f32_e32 v84, v84
	v_exp_f32_e32 v85, v85
	v_exp_f32_e32 v86, v86
	v_exp_f32_e32 v87, v87
	v_exp_f32_e32 v88, v88
	v_exp_f32_e32 v89, v89
	v_exp_f32_e32 v90, v90
	v_exp_f32_e32 v91, v91
	v_exp_f32_e32 v92, v92
	v_exp_f32_e32 v93, v93
	v_exp_f32_e32 v94, v94
	v_exp_f32_e32 v95, v95
	v_pk_add_f32 v[186:187], v[80:81], v[82:83]
	v_pk_add_f32 v[188:189], v[84:85], v[86:87]
	v_pk_add_f32 v[190:191], v[88:89], v[90:91]
	v_pk_add_f32 v[192:193], v[92:93], v[94:95]
	v_pk_add_f32 v[186:187], v[186:187], v[188:189]
	v_pk_add_f32 v[190:191], v[190:191], v[192:193]
	v_pk_add_f32 v[186:187], v[186:187], v[190:191]
	v_add_f32_e32 v186, v186, v187
	v_add_f32_e32 v185, v185, v186
	v_cvt_pk_bf16_f32 v80, v80, v81
	v_cvt_pk_bf16_f32 v81, v82, v83
	v_cvt_pk_bf16_f32 v82, v84, v85
	v_cvt_pk_bf16_f32 v83, v86, v87
	v_cvt_pk_bf16_f32 v84, v88, v89
	v_cvt_pk_bf16_f32 v85, v90, v91
	v_cvt_pk_bf16_f32 v86, v92, v93
	v_cvt_pk_bf16_f32 v87, v94, v95
	s_waitcnt vmcnt(8)
	s_nop 0
	v_mfma_f32_32x32x16_bf16 v[64:79], v[144:147], v[80:83], v[64:79]
	v_mfma_f32_32x32x16_bf16 v[32:47], v[148:151], v[80:83], v[32:47]
	v_mfma_f32_32x32x16_bf16 v[64:79], v[152:155], v[84:87], v[64:79]
	v_mfma_f32_32x32x16_bf16 v[32:47], v[156:159], v[84:87], v[32:47]
	s_waitcnt lgkmcnt(0)
	v_pk_add_f32 v[228:229], v[228:229], v[202:203]
	v_pk_add_f32 v[230:231], v[230:231], v[252:253]
	v_cndmask_b32_e64 v228, v182, v228, s[66:67]
	v_cndmask_b32_e64 v229, v182, v229, s[94:95]
	v_cndmask_b32_e64 v230, v182, v230, s[96:97]
	v_cndmask_b32_e64 v231, v182, v231, s[98:99]
	v_exp_f32_e32 v228, v228
	v_exp_f32_e32 v229, v229
	v_exp_f32_e32 v230, v230
	v_exp_f32_e32 v231, v231
	v_mov_b32_e32 v224, 0
	v_mov_b32_e32 v225, 0
	v_pk_add_f32 v[202:203], v[228:229], v[230:231]
	v_cvt_pk_bf16_f32 v226, v228, v229
	v_cvt_pk_bf16_f32 v227, v230, v231
	v_add_f32_e32 v202, v202, v203
	v_add_f32_e32 v184, v184, v202
	s_nop 1
	v_mfma_f32_32x32x16_bf16 v[16:31], v[152:155], v[224:227], v[16:31]
	v_mfma_f32_32x32x16_bf16 v[0:15], v[156:159], v[224:227], v[0:15]
	ds_read2_b32 v[202:203], v255 offset0:64 offset1:65
	ds_read2_b32 v[252:253], v255 offset0:66 offset1:67
	ds_read2_b32 v[186:187], v255 offset0:32 offset1:33
	ds_read2_b32 v[188:189], v255 offset0:34 offset1:35
	ds_read2_b32 v[190:191], v255 offset0:40 offset1:41
	ds_read2_b32 v[192:193], v255 offset0:42 offset1:43
	ds_read2_b32 v[194:195], v255 offset0:48 offset1:49
	ds_read2_b32 v[196:197], v255 offset0:50 offset1:51
	ds_read2_b32 v[198:199], v255 offset0:56 offset1:57
	ds_read2_b32 v[200:201], v255 offset0:58 offset1:59
	ds_read_b128 v[204:207], v168 offset:4096
	ds_read_b128 v[208:211], v168 offset:5120
	ds_read_b128 v[212:215], v168 offset:6144
	ds_read_b128 v[248:251], v168 offset:7168
	v_add_u32_e32 v255, 0x200, v255
	s_waitcnt vmcnt(4)
	v_mfma_f32_32x32x16_bf16 v[80:95], v[136:139], v[96:99], v[48:63]
	v_mfma_f32_32x32x16_bf16 v[216:231], v[136:139], v[104:107], v[48:63]
	v_mfma_f32_32x32x16_bf16 v[80:95], v[132:135], v[100:103], v[80:95]
	v_mfma_f32_32x32x16_bf16 v[216:231], v[132:135], v[108:111], v[216:231]
	v_mfma_f32_32x32x16_bf16 v[80:95], v[140:143], v[112:115], v[80:95]
	v_mfma_f32_32x32x16_bf16 v[216:231], v[140:143], v[120:123], v[216:231]
	v_mfma_f32_32x32x16_bf16 v[80:95], v[128:131], v[116:119], v[80:95]
	v_mfma_f32_32x32x16_bf16 v[216:231], v[128:131], v[124:127], v[216:231]
	global_load_dwordx4 v[136:139], v168, s[54:55]
	global_load_dwordx4 v[132:135], v168, s[54:55] offset:1024
	global_load_dwordx4 v[140:143], v168, s[54:55] offset:2048
	global_load_dwordx4 v[128:131], v168, s[54:55] offset:3072
	global_load_dwordx4 v[144:147], v168, s[56:57]
	global_load_dwordx4 v[148:151], v168, s[56:57] offset:1024
	global_load_dwordx4 v[152:155], v168, s[56:57] offset:2048
	global_load_dwordx4 v[156:159], v168, s[56:57] offset:3072
	s_add_u32 s54, s54, 0x1000
	s_addc_u32 s55, s55, 0
	s_add_u32 s56, s56, 0x1000
	s_addc_u32 s57, s57, 0
	s_waitcnt lgkmcnt(12)
	v_pk_add_f32 v[80:81], v[80:81], v[202:203]
	v_pk_add_f32 v[82:83], v[82:83], v[252:253]
	v_cndmask_b32_e64 v80, v182, v80, s[58:59]
	v_cndmask_b32_e64 v81, v182, v81, s[60:61]
	v_cndmask_b32_e64 v82, v182, v82, s[62:63]
	v_cndmask_b32_e64 v83, v182, v83, s[64:65]
	v_exp_f32_e32 v80, v80
	v_exp_f32_e32 v81, v81
	v_exp_f32_e32 v82, v82
	v_exp_f32_e32 v83, v83
	s_nop 0
	v_pk_add_f32 v[202:203], v[80:81], v[82:83]
	v_cvt_pk_bf16_f32 v80, v80, v81
	v_cvt_pk_bf16_f32 v81, v82, v83
	v_mov_b32_e32 v82, 0
	v_mov_b32_e32 v83, 0
	v_add_f32_e32 v202, v202, v203
	v_add_f32_e32 v185, v185, v202
	s_waitcnt vmcnt(8)
	s_nop 0
	v_mfma_f32_32x32x16_bf16 v[64:79], v[232:235], v[80:83], v[64:79]
	v_mfma_f32_32x32x16_bf16 v[32:47], v[236:239], v[80:83], v[32:47]
	s_waitcnt lgkmcnt(0)
	v_pk_add_f32 v[216:217], v[216:217], v[186:187]
	v_pk_add_f32 v[218:219], v[218:219], v[188:189]
	v_pk_add_f32 v[220:221], v[220:221], v[190:191]
	v_pk_add_f32 v[222:223], v[222:223], v[192:193]
	v_pk_add_f32 v[224:225], v[224:225], v[194:195]
	v_pk_add_f32 v[226:227], v[226:227], v[196:197]
	v_pk_add_f32 v[228:229], v[228:229], v[198:199]
	v_pk_add_f32 v[230:231], v[230:231], v[200:201]
	v_pk_add_f32 v[216:217], v[216:217], v[204:205]
	v_pk_add_f32 v[218:219], v[218:219], v[206:207]
	v_pk_add_f32 v[220:221], v[220:221], v[208:209]
	v_pk_add_f32 v[222:223], v[222:223], v[210:211]
	v_pk_add_f32 v[224:225], v[224:225], v[212:213]
	v_pk_add_f32 v[226:227], v[226:227], v[214:215]
	v_pk_add_f32 v[228:229], v[228:229], v[248:249]
	v_pk_add_f32 v[230:231], v[230:231], v[250:251]
	v_exp_f32_e32 v216, v216
	v_exp_f32_e32 v217, v217
	v_exp_f32_e32 v218, v218
	v_exp_f32_e32 v219, v219
	v_exp_f32_e32 v220, v220
	v_exp_f32_e32 v221, v221
	v_exp_f32_e32 v222, v222
	v_exp_f32_e32 v223, v223
	v_exp_f32_e32 v224, v224
	v_exp_f32_e32 v225, v225
	v_exp_f32_e32 v226, v226
	v_exp_f32_e32 v227, v227
	v_exp_f32_e32 v228, v228
	v_exp_f32_e32 v229, v229
	v_exp_f32_e32 v230, v230
	v_exp_f32_e32 v231, v231
	v_pk_add_f32 v[186:187], v[216:217], v[218:219]
	v_pk_add_f32 v[188:189], v[220:221], v[222:223]
	v_pk_add_f32 v[190:191], v[224:225], v[226:227]
	v_pk_add_f32 v[192:193], v[228:229], v[230:231]
	v_pk_add_f32 v[186:187], v[186:187], v[188:189]
	v_pk_add_f32 v[190:191], v[190:191], v[192:193]
	v_pk_add_f32 v[186:187], v[186:187], v[190:191]
	v_add_f32_e32 v186, v186, v187
	v_add_f32_e32 v184, v184, v186
	v_cvt_pk_bf16_f32 v216, v216, v217
	v_cvt_pk_bf16_f32 v217, v218, v219
	v_cvt_pk_bf16_f32 v218, v220, v221
	v_cvt_pk_bf16_f32 v219, v222, v223
	v_cvt_pk_bf16_f32 v220, v224, v225
	v_cvt_pk_bf16_f32 v221, v226, v227
	v_cvt_pk_bf16_f32 v222, v228, v229
	v_cvt_pk_bf16_f32 v223, v230, v231
	s_nop 1
	v_mfma_f32_32x32x16_bf16 v[16:31], v[232:235], v[216:219], v[16:31]
	v_mfma_f32_32x32x16_bf16 v[0:15], v[236:239], v[216:219], v[0:15]
	v_mfma_f32_32x32x16_bf16 v[16:31], v[240:243], v[220:223], v[16:31]
	v_mfma_f32_32x32x16_bf16 v[0:15], v[244:247], v[220:223], v[0:15]
	s_add_i32 s53, s53, 1
	s_cmp_lt_u32 s53, 7
	s_cbranch_scc1 .Lao_win_loop
	ds_read2_b32 v[186:187], v255 offset0:32 offset1:33
	ds_read2_b32 v[188:189], v255 offset0:34 offset1:35
	ds_read2_b32 v[190:191], v255 offset0:40 offset1:41
	ds_read2_b32 v[192:193], v255 offset0:42 offset1:43
	ds_read2_b32 v[194:195], v255 offset0:48 offset1:49
	ds_read2_b32 v[196:197], v255 offset0:50 offset1:51
	ds_read2_b32 v[198:199], v255 offset0:56 offset1:57
	ds_read2_b32 v[200:201], v255 offset0:58 offset1:59
	ds_read_b128 v[204:207], v168 offset:0
	ds_read_b128 v[208:211], v168 offset:1024
	ds_read_b128 v[212:215], v168 offset:2048
	ds_read_b128 v[248:251], v168 offset:3072
	ds_read2_b32 v[202:203], v255 offset0:24 offset1:25
	ds_read2_b32 v[252:253], v255 offset0:26 offset1:27
	s_waitcnt vmcnt(4)
	v_mfma_f32_32x32x16_bf16 v[80:95], v[136:139], v[96:99], v[48:63]
	v_mfma_f32_32x32x16_bf16 v[216:231], v[136:139], v[104:107], v[48:63]
	v_mfma_f32_32x32x16_bf16 v[80:95], v[132:135], v[100:103], v[80:95]
	v_mfma_f32_32x32x16_bf16 v[216:231], v[132:135], v[108:111], v[216:231]
	v_mfma_f32_32x32x16_bf16 v[80:95], v[140:143], v[112:115], v[80:95]
	v_mfma_f32_32x32x16_bf16 v[216:231], v[140:143], v[120:123], v[216:231]
	v_mfma_f32_32x32x16_bf16 v[80:95], v[128:131], v[116:119], v[80:95]
	v_mfma_f32_32x32x16_bf16 v[216:231], v[128:131], v[124:127], v[216:231]
	global_load_dwordx4 v[136:139], v168, s[54:55]
	global_load_dwordx4 v[132:135], v168, s[54:55] offset:1024
	global_load_dwordx4 v[140:143], v168, s[54:55] offset:2048
	global_load_dwordx4 v[128:131], v168, s[54:55] offset:3072
	global_load_dwordx4 v[232:235], v168, s[56:57]
	global_load_dwordx4 v[236:239], v168, s[56:57] offset:1024
	global_load_dwordx4 v[240:243], v168, s[56:57] offset:2048
	global_load_dwordx4 v[244:247], v168, s[56:57] offset:3072
	s_add_u32 s54, s54, 0x1000
	s_addc_u32 s55, s55, 0
	s_add_u32 s56, s56, 0x1000
	s_addc_u32 s57, s57, 0
	s_waitcnt lgkmcnt(2)
	v_pk_add_f32 v[80:81], v[80:81], v[186:187]
	v_pk_add_f32 v[82:83], v[82:83], v[188:189]
	v_pk_add_f32 v[84:85], v[84:85], v[190:191]
	v_pk_add_f32 v[86:87], v[86:87], v[192:193]
	v_pk_add_f32 v[88:89], v[88:89], v[194:195]
	v_pk_add_f32 v[90:91], v[90:91], v[196:197]
	v_pk_add_f32 v[92:93], v[92:93], v[198:199]
	v_pk_add_f32 v[94:95], v[94:95], v[200:201]
	v_pk_add_f32 v[80:81], v[80:81], v[204:205]
	v_pk_add_f32 v[82:83], v[82:83], v[206:207]
	v_pk_add_f32 v[84:85], v[84:85], v[208:209]
	v_pk_add_f32 v[86:87], v[86:87], v[210:211]
	v_pk_add_f32 v[88:89], v[88:89], v[212:213]
	v_pk_add_f32 v[90:91], v[90:91], v[214:215]
	v_pk_add_f32 v[92:93], v[92:93], v[248:249]
	v_pk_add_f32 v[94:95], v[94:95], v[250:251]
	v_exp_f32_e32 v80, v80
	v_exp_f32_e32 v81, v81
	v_exp_f32_e32 v82, v82
	v_exp_f32_e32 v83, v83
	v_exp_f32_e32 v84, v84
	v_exp_f32_e32 v85, v85
	v_exp_f32_e32 v86, v86
	v_exp_f32_e32 v87, v87
	v_exp_f32_e32 v88, v88
	v_exp_f32_e32 v89, v89
	v_exp_f32_e32 v90, v90
	v_exp_f32_e32 v91, v91
	v_exp_f32_e32 v92, v92
	v_exp_f32_e32 v93, v93
	v_exp_f32_e32 v94, v94
	v_exp_f32_e32 v95, v95
	v_pk_add_f32 v[186:187], v[80:81], v[82:83]
	v_pk_add_f32 v[188:189], v[84:85], v[86:87]
	v_pk_add_f32 v[190:191], v[88:89], v[90:91]
	v_pk_add_f32 v[192:193], v[92:93], v[94:95]
	v_pk_add_f32 v[186:187], v[186:187], v[188:189]
	v_pk_add_f32 v[190:191], v[190:191], v[192:193]
	v_pk_add_f32 v[186:187], v[186:187], v[190:191]
	v_add_f32_e32 v186, v186, v187
	v_add_f32_e32 v185, v185, v186
	v_cvt_pk_bf16_f32 v80, v80, v81
	v_cvt_pk_bf16_f32 v81, v82, v83
	v_cvt_pk_bf16_f32 v82, v84, v85
	v_cvt_pk_bf16_f32 v83, v86, v87
	v_cvt_pk_bf16_f32 v84, v88, v89
	v_cvt_pk_bf16_f32 v85, v90, v91
	v_cvt_pk_bf16_f32 v86, v92, v93
	v_cvt_pk_bf16_f32 v87, v94, v95
	s_waitcnt vmcnt(8)
	s_nop 0
	v_mfma_f32_32x32x16_bf16 v[64:79], v[144:147], v[80:83], v[64:79]
	v_mfma_f32_32x32x16_bf16 v[32:47], v[148:151], v[80:83], v[32:47]
	v_mfma_f32_32x32x16_bf16 v[64:79], v[152:155], v[84:87], v[64:79]
	v_mfma_f32_32x32x16_bf16 v[32:47], v[156:159], v[84:87], v[32:47]
	s_waitcnt lgkmcnt(0)
	v_pk_add_f32 v[228:229], v[228:229], v[202:203]
	v_pk_add_f32 v[230:231], v[230:231], v[252:253]
	v_cndmask_b32_e64 v228, v182, v228, s[66:67]
	v_cndmask_b32_e64 v229, v182, v229, s[94:95]
	v_cndmask_b32_e64 v230, v182, v230, s[96:97]
	v_cndmask_b32_e64 v231, v182, v231, s[98:99]
	v_exp_f32_e32 v228, v228
	v_exp_f32_e32 v229, v229
	v_exp_f32_e32 v230, v230
	v_exp_f32_e32 v231, v231
	v_mov_b32_e32 v224, 0
	v_mov_b32_e32 v225, 0
	v_pk_add_f32 v[202:203], v[228:229], v[230:231]
	v_cvt_pk_bf16_f32 v226, v228, v229
	v_cvt_pk_bf16_f32 v227, v230, v231
	v_add_f32_e32 v202, v202, v203
	v_add_f32_e32 v184, v184, v202
	s_nop 1
	v_mfma_f32_32x32x16_bf16 v[16:31], v[152:155], v[224:227], v[16:31]
	v_mfma_f32_32x32x16_bf16 v[0:15], v[156:159], v[224:227], v[0:15]
	s_mov_b32 s32, 1
	ds_read2_b32 v[202:203], v255 offset0:64 offset1:65
	ds_read2_b32 v[252:253], v255 offset0:66 offset1:67
	ds_read2_b32 v[186:187], v255 offset0:32 offset1:33
	ds_read2_b32 v[188:189], v255 offset0:34 offset1:35
	ds_read2_b32 v[190:191], v255 offset0:40 offset1:41
	ds_read2_b32 v[192:193], v255 offset0:42 offset1:43
	ds_read2_b32 v[194:195], v255 offset0:48 offset1:49
	ds_read2_b32 v[196:197], v255 offset0:50 offset1:51
	ds_read2_b32 v[198:199], v255 offset0:56 offset1:57
	ds_read2_b32 v[200:201], v255 offset0:58 offset1:59
	ds_read_b128 v[204:207], v168 offset:4096
	ds_read_b128 v[208:211], v168 offset:5120
	ds_read_b128 v[212:215], v168 offset:6144
	ds_read_b128 v[248:251], v168 offset:7168
	v_add_u32_e32 v255, 0x200, v255
	s_waitcnt vmcnt(4)
	v_mfma_f32_32x32x16_bf16 v[80:95], v[136:139], v[96:99], v[48:63]
	v_mfma_f32_32x32x16_bf16 v[216:231], v[136:139], v[104:107], v[48:63]
	v_mfma_f32_32x32x16_bf16 v[80:95], v[132:135], v[100:103], v[80:95]
	v_mfma_f32_32x32x16_bf16 v[216:231], v[132:135], v[108:111], v[216:231]
	v_mfma_f32_32x32x16_bf16 v[80:95], v[140:143], v[112:115], v[80:95]
	v_mfma_f32_32x32x16_bf16 v[216:231], v[140:143], v[120:123], v[216:231]
	v_mfma_f32_32x32x16_bf16 v[80:95], v[128:131], v[116:119], v[80:95]
	v_mfma_f32_32x32x16_bf16 v[216:231], v[128:131], v[124:127], v[216:231]
	s_cmp_lg_u32 s32, 0
	s_cbranch_scc1 .Lao_skip_w1l
	global_load_dwordx4 v[136:139], v168, s[54:55]
	global_load_dwordx4 v[132:135], v168, s[54:55] offset:1024
	global_load_dwordx4 v[140:143], v168, s[54:55] offset:2048
	global_load_dwordx4 v[128:131], v168, s[54:55] offset:3072
	global_load_dwordx4 v[144:147], v168, s[56:57]
	global_load_dwordx4 v[148:151], v168, s[56:57] offset:1024
	global_load_dwordx4 v[152:155], v168, s[56:57] offset:2048
	global_load_dwordx4 v[156:159], v168, s[56:57] offset:3072
	s_add_u32 s54, s54, 0x1000
	s_addc_u32 s55, s55, 0
	s_add_u32 s56, s56, 0x1000
	s_addc_u32 s57, s57, 0
	s_branch .Lao_join_w1l
.Lao_skip_w1l:
	s_waitcnt vmcnt(0)
	s_nop 7
.Lao_join_w1l:
	s_waitcnt lgkmcnt(12)
	v_pk_add_f32 v[80:81], v[80:81], v[202:203]
	v_pk_add_f32 v[82:83], v[82:83], v[252:253]
	v_cndmask_b32_e64 v80, v182, v80, s[58:59]
	v_cndmask_b32_e64 v81, v182, v81, s[60:61]
	v_cndmask_b32_e64 v82, v182, v82, s[62:63]
	v_cndmask_b32_e64 v83, v182, v83, s[64:65]
	v_exp_f32_e32 v80, v80
	v_exp_f32_e32 v81, v81
	v_exp_f32_e32 v82, v82
	v_exp_f32_e32 v83, v83
	s_nop 0
	v_pk_add_f32 v[202:203], v[80:81], v[82:83]
	v_cvt_pk_bf16_f32 v80, v80, v81
	v_cvt_pk_bf16_f32 v81, v82, v83
	v_mov_b32_e32 v82, 0
	v_mov_b32_e32 v83, 0
	v_add_f32_e32 v202, v202, v203
	v_add_f32_e32 v185, v185, v202
	s_waitcnt vmcnt(8)
	s_nop 0
	v_mfma_f32_32x32x16_bf16 v[64:79], v[232:235], v[80:83], v[64:79]
	v_mfma_f32_32x32x16_bf16 v[32:47], v[236:239], v[80:83], v[32:47]
	s_waitcnt lgkmcnt(0)
	v_pk_add_f32 v[216:217], v[216:217], v[186:187]
	v_pk_add_f32 v[218:219], v[218:219], v[188:189]
	v_pk_add_f32 v[220:221], v[220:221], v[190:191]
	v_pk_add_f32 v[222:223], v[222:223], v[192:193]
	v_pk_add_f32 v[224:225], v[224:225], v[194:195]
	v_pk_add_f32 v[226:227], v[226:227], v[196:197]
	v_pk_add_f32 v[228:229], v[228:229], v[198:199]
	v_pk_add_f32 v[230:231], v[230:231], v[200:201]
	v_pk_add_f32 v[216:217], v[216:217], v[204:205]
	v_pk_add_f32 v[218:219], v[218:219], v[206:207]
	v_pk_add_f32 v[220:221], v[220:221], v[208:209]
	v_pk_add_f32 v[222:223], v[222:223], v[210:211]
	v_pk_add_f32 v[224:225], v[224:225], v[212:213]
	v_pk_add_f32 v[226:227], v[226:227], v[214:215]
	v_pk_add_f32 v[228:229], v[228:229], v[248:249]
	v_pk_add_f32 v[230:231], v[230:231], v[250:251]
	v_exp_f32_e32 v216, v216
	v_exp_f32_e32 v217, v217
	v_exp_f32_e32 v218, v218
	v_exp_f32_e32 v219, v219
	v_exp_f32_e32 v220, v220
	v_exp_f32_e32 v221, v221
	v_exp_f32_e32 v222, v222
	v_exp_f32_e32 v223, v223
	v_exp_f32_e32 v224, v224
	v_exp_f32_e32 v225, v225
	v_exp_f32_e32 v226, v226
	v_exp_f32_e32 v227, v227
	v_exp_f32_e32 v228, v228
	v_exp_f32_e32 v229, v229
	v_exp_f32_e32 v230, v230
	v_exp_f32_e32 v231, v231
	v_pk_add_f32 v[186:187], v[216:217], v[218:219]
	v_pk_add_f32 v[188:189], v[220:221], v[222:223]
	v_pk_add_f32 v[190:191], v[224:225], v[226:227]
	v_pk_add_f32 v[192:193], v[228:229], v[230:231]
	v_pk_add_f32 v[186:187], v[186:187], v[188:189]
	v_pk_add_f32 v[190:191], v[190:191], v[192:193]
	v_pk_add_f32 v[186:187], v[186:187], v[190:191]
	v_add_f32_e32 v186, v186, v187
	v_add_f32_e32 v184, v184, v186
	v_cvt_pk_bf16_f32 v216, v216, v217
	v_cvt_pk_bf16_f32 v217, v218, v219
	v_cvt_pk_bf16_f32 v218, v220, v221
	v_cvt_pk_bf16_f32 v219, v222, v223
	v_cvt_pk_bf16_f32 v220, v224, v225
	v_cvt_pk_bf16_f32 v221, v226, v227
	v_cvt_pk_bf16_f32 v222, v228, v229
	v_cvt_pk_bf16_f32 v223, v230, v231
	s_nop 1
	v_mfma_f32_32x32x16_bf16 v[16:31], v[232:235], v[216:219], v[16:31]
	v_mfma_f32_32x32x16_bf16 v[0:15], v[236:239], v[216:219], v[0:15]
	v_mfma_f32_32x32x16_bf16 v[16:31], v[240:243], v[220:223], v[16:31]
	v_mfma_f32_32x32x16_bf16 v[0:15], v[244:247], v[220:223], v[0:15]
	s_branch .LBB0_1084
